# sub-layer-norm butterfly sums: lane xor 1,2,4,8 steps through DPP instead of ds_bpermute round trips
# baseline (speedup 1.0000x reference)
; DI int crow(int r, int hi) { return (r & 3) + 8 * (r >> 2) + 4 * hi; }
; DI u16 f2bf(float x) { return (u16)(cvtpk(x, x) & 0xffffu); }
; template <int PROBE, int MODE>
; DI void dattn_body(const u16* __restrict__ Qb, const u16* __restrict__ Kh, const u16* __restrict__ Vh, u16* __restrict__ Ob, const u16* __restrict__ O1, float lam, const float* __restrict__ subg, int seq, int q0, float kmax2, char* lds) {
;     ...
;   float rli[16];
; #pragma unroll
;   for (int r = 0; r < 16; ++r) rli[r] = __builtin_amdgcn_rcpf(lsum[wid * 32 + crow(r, hi)] + lsum[(wid ^ 1) * 32 + crow(r, hi)]);
;   u16* Ow = Ob + (long)(rg * 32) * 4096 + kh * 128;
;   if (PROBE) {
;     float acc_ = 0.f;
; #pragma unroll
;     for (int r = 0; r < 16; ++r)
; #pragma unroll
;       for (int d0 = 0; d0 < 4; ++d0) acc_ += o[d0][r] * rli[r];
;     if (acc_ == 123.456f && seq < 0) Ow[0] = f2bf(acc_);
;     return;
;   }
;   (void)Ow;
;   {
;     char* Ot = lds;
;     constexpr int UOROW = 528;
; #pragma unroll
;     for (int r = 0; r < 16; ++r) { const int orow = rg * 32 + crow(r, hi);
; #pragma unroll
;       for (int d0 = 0; d0 < 4; ++d0) *reinterpret_cast<u16*>(Ot + orow * UOROW + (kh * 128 + d0 * 32 + r32) * 2) = f2bf(o[d0][r] * rli[r]); }
.LBB0_226:
	s_or_b64 exec, exec, s[0:1]
	v_add_u32_e32 v82, s82, v64
	v_lshl_add_u32 v83, v207, 7, s82
	v_lshlrev_b32_e32 v68, 2, v206
	v_add_u32_e32 v84, v82, v68
	v_add_u32_e32 v85, v83, v68
	s_waitcnt lgkmcnt(0)
	s_barrier
	ds_read_b128 v[64:67], v84
	ds_read_b128 v[68:71], v85
	ds_read_b128 v[72:75], v84 offset:32
	ds_read_b128 v[76:79], v85 offset:32
	ds_read_b32 v87, v84 offset:108
	v_lshlrev_b32_e32 v86, 3, v175
	s_mov_b64 s[0:1], 0x10000
	s_movk_i32 s87, 0x80
	s_waitcnt lgkmcnt(3)
	v_add_f32_e32 v64, v64, v68
	v_rcp_f32_e32 v88, v64
	v_add_f32_e32 v64, v65, v69
	v_rcp_f32_e32 v89, v64
	v_add_f32_e32 v64, v66, v70
	s_waitcnt lgkmcnt(1)
	v_add_f32_e32 v68, v72, v76
	v_rcp_f32_e32 v90, v64
	v_add_f32_e32 v64, v67, v71
	v_rcp_f32_e32 v76, v68
	v_add_f32_e32 v68, v73, v77
	v_rcp_f32_e32 v91, v64
	ds_read_b128 v[64:67], v85 offset:64
	v_rcp_f32_e32 v77, v68
	ds_read_b128 v[68:71], v84 offset:64
	v_add_f32_e32 v72, v74, v78
	v_rcp_f32_e32 v74, v72
	v_add_f32_e32 v72, v75, v79
	v_rcp_f32_e32 v75, v72
	ds_read2_b32 v[72:73], v84 offset0:25 offset1:26
	s_waitcnt lgkmcnt(1)
	v_add_f32_e32 v64, v68, v64
	v_rcp_f32_e32 v68, v64
	v_add_f32_e32 v64, v69, v65
	v_rcp_f32_e32 v69, v64
	v_add_f32_e32 v64, v70, v66
	v_rcp_f32_e32 v66, v64
	v_lshlrev_b32_e32 v64, 2, v205
	v_add_u32_e32 v65, v82, v64
	v_add_u32_e32 v64, v83, v64
	ds_read_b32 v70, v65
	ds_read_b32 v78, v64
	ds_read2_b32 v[64:65], v85 offset0:25 offset1:26
	v_add_f32_e32 v67, v71, v67
	ds_read_b32 v71, v85 offset:108
	v_mul_f32_e32 v0, v0, v88
	s_waitcnt lgkmcnt(2)
	v_add_f32_e32 v70, v70, v78
	s_waitcnt lgkmcnt(1)
	v_add_f32_e32 v64, v72, v64
	v_add_u32_e32 v72, v206, v197
	v_mul_lo_u32 v72, v72, s28
	v_add_f32_e32 v65, v73, v65
	v_add_u32_e32 v72, 16, v72
	v_lshlrev_b32_e32 v73, 8, v195
	v_lshlrev_b32_e32 v78, 1, v192
	v_cvt_pk_bf16_f32 v0, v0, v0
	v_add3_u32 v72, v72, v73, v78
	ds_write_b16 v72, v0
	v_mul_f32_e32 v0, v16, v88
	v_cvt_pk_bf16_f32 v0, v0, v0
	ds_write_b16 v72, v0 offset:64
	v_mul_f32_e32 v0, v32, v88
	v_cvt_pk_bf16_f32 v0, v0, v0
	ds_write_b16 v72, v0 offset:128
	v_mul_f32_e32 v0, v48, v88
	v_cvt_pk_bf16_f32 v0, v0, v0
	ds_write_b16 v72, v0 offset:192
	v_mul_f32_e32 v0, v1, v89
	v_cvt_pk_bf16_f32 v0, v0, v0
	ds_write_b16 v72, v0 offset:528
	v_mul_f32_e32 v0, v17, v89
	v_cvt_pk_bf16_f32 v0, v0, v0
	ds_write_b16 v72, v0 offset:592
	v_mul_f32_e32 v0, v33, v89
	v_cvt_pk_bf16_f32 v0, v0, v0
	ds_write_b16 v72, v0 offset:656
	v_mul_f32_e32 v0, v49, v89
	v_cvt_pk_bf16_f32 v0, v0, v0
	ds_write_b16 v72, v0 offset:720
	v_mul_f32_e32 v0, v2, v90
	v_cvt_pk_bf16_f32 v0, v0, v0
	ds_write_b16 v72, v0 offset:1056
	v_mul_f32_e32 v0, v18, v90
	v_cvt_pk_bf16_f32 v0, v0, v0
	ds_write_b16 v72, v0 offset:1120
	v_mul_f32_e32 v0, v34, v90
	v_cvt_pk_bf16_f32 v0, v0, v0
	ds_write_b16 v72, v0 offset:1184
	v_mul_f32_e32 v0, v50, v90
	v_cvt_pk_bf16_f32 v0, v0, v0
	ds_write_b16 v72, v0 offset:1248
	v_mul_f32_e32 v0, v3, v91
	v_cvt_pk_bf16_f32 v0, v0, v0
	ds_write_b16 v72, v0 offset:1584
	v_mul_f32_e32 v0, v19, v91
	v_cvt_pk_bf16_f32 v0, v0, v0
	ds_write_b16 v72, v0 offset:1648
	v_mul_f32_e32 v0, v35, v91
	v_cvt_pk_bf16_f32 v0, v0, v0
	ds_write_b16 v72, v0 offset:1712
	v_mul_f32_e32 v0, v51, v91
	v_cvt_pk_bf16_f32 v0, v0, v0
	ds_write_b16 v72, v0 offset:1776
	v_mul_f32_e32 v0, v4, v76
	v_cvt_pk_bf16_f32 v0, v0, v0
	ds_write_b16 v72, v0 offset:4224
	v_mul_f32_e32 v0, v20, v76
	v_cvt_pk_bf16_f32 v0, v0, v0
	ds_write_b16 v72, v0 offset:4288
	v_mul_f32_e32 v0, v36, v76
	v_cvt_pk_bf16_f32 v0, v0, v0
	ds_write_b16 v72, v0 offset:4352
	v_mul_f32_e32 v0, v52, v76
	v_cvt_pk_bf16_f32 v0, v0, v0
	ds_write_b16 v72, v0 offset:4416
	v_mul_f32_e32 v0, v5, v77
	v_cvt_pk_bf16_f32 v0, v0, v0
	ds_write_b16 v72, v0 offset:4752
	v_mul_f32_e32 v0, v21, v77
	v_cvt_pk_bf16_f32 v0, v0, v0
	ds_write_b16 v72, v0 offset:4816
	v_mul_f32_e32 v0, v37, v77
	v_cvt_pk_bf16_f32 v0, v0, v0
	ds_write_b16 v72, v0 offset:4880
	v_mul_f32_e32 v0, v53, v77
	v_cvt_pk_bf16_f32 v0, v0, v0
	ds_write_b16 v72, v0 offset:4944
	v_mul_f32_e32 v0, v6, v74
	v_cvt_pk_bf16_f32 v0, v0, v0
	ds_write_b16 v72, v0 offset:5280
	v_mul_f32_e32 v0, v22, v74
	v_cvt_pk_bf16_f32 v0, v0, v0
	ds_write_b16 v72, v0 offset:5344
	v_mul_f32_e32 v0, v38, v74
	v_cvt_pk_bf16_f32 v0, v0, v0
	ds_write_b16 v72, v0 offset:5408
	v_mul_f32_e32 v0, v54, v74
	v_cvt_pk_bf16_f32 v0, v0, v0
	ds_write_b16 v72, v0 offset:5472
	v_mul_f32_e32 v0, v7, v75
	v_cvt_pk_bf16_f32 v0, v0, v0
	ds_write_b16 v72, v0 offset:5808
	v_mul_f32_e32 v0, v23, v75
	v_cvt_pk_bf16_f32 v0, v0, v0
	ds_write_b16 v72, v0 offset:5872
	v_mul_f32_e32 v0, v39, v75
	v_cvt_pk_bf16_f32 v0, v0, v0
	ds_write_b16 v72, v0 offset:5936
	v_mul_f32_e32 v0, v55, v75
	v_cvt_pk_bf16_f32 v0, v0, v0
	ds_write_b16 v72, v0 offset:6000
	v_mul_f32_e32 v0, v8, v68
	v_cvt_pk_bf16_f32 v0, v0, v0
	ds_write_b16 v72, v0 offset:8448
	v_mul_f32_e32 v0, v24, v68
	v_cvt_pk_bf16_f32 v0, v0, v0
	ds_write_b16 v72, v0 offset:8512
	v_mul_f32_e32 v0, v40, v68
	v_cvt_pk_bf16_f32 v0, v0, v0
	ds_write_b16 v72, v0 offset:8576
	v_mul_f32_e32 v0, v56, v68
	v_cvt_pk_bf16_f32 v0, v0, v0
	ds_write_b16 v72, v0 offset:8640
	v_mul_f32_e32 v0, v9, v69
	v_cvt_pk_bf16_f32 v0, v0, v0
	ds_write_b16 v72, v0 offset:8976
	v_mul_f32_e32 v0, v25, v69
	v_cvt_pk_bf16_f32 v0, v0, v0
	ds_write_b16 v72, v0 offset:9040
	v_mul_f32_e32 v0, v41, v69
	v_cvt_pk_bf16_f32 v0, v0, v0
	ds_write_b16 v72, v0 offset:9104
	v_mul_f32_e32 v0, v57, v69
	v_cvt_pk_bf16_f32 v0, v0, v0
	ds_write_b16 v72, v0 offset:9168
	v_mul_f32_e32 v0, v10, v66
	v_cvt_pk_bf16_f32 v0, v0, v0
	ds_write_b16 v72, v0 offset:9504
	v_mul_f32_e32 v0, v26, v66
	v_cvt_pk_bf16_f32 v0, v0, v0
	v_rcp_f32_e32 v67, v67
; DI u16 f2bf(float x) { return (u16)(cvtpk(x, x) & 0xffffu); }
; DI f32x4 bf4lo(u32x4 w) { f32x4 r = {bflo(w[0]), bfhi(w[0]), bflo(w[1]), bfhi(w[1])}; return r; }
; DI f32x4 bf4hi(u32x4 w) { f32x4 r = {bflo(w[2]), bfhi(w[2]), bflo(w[3]), bfhi(w[3])}; return r; }
; template <int PROBE, int MODE>
; DI void dattn_body(const u16* __restrict__ Qb, const u16* __restrict__ Kh, const u16* __restrict__ Vh, u16* __restrict__ Ob, const u16* __restrict__ O1, float lam, const float* __restrict__ subg, int seq, int q0, float kmax2, char* lds) {
;     ...
;       for (int d0 = 0; d0 < 4; ++d0) *reinterpret_cast<u16*>(Ot + orow * UOROW + (kh * 128 + d0 * 32 + r32) * 2) = f2bf(o[d0][r] * rli[r]); }
;     __syncthreads();
;     if (MODE == 0) {
; #pragma unroll
;       for (int it = 0; it < 8; ++it) {
;         const int row = (tid >> 5) + 16 * it, c8 = (tid & 31) * 8;
;         *reinterpret_cast<bf16x8*>(Ob + (long)row * DM + c8) = *reinterpret_cast<const bf16x8*>(Ot + row * UOROW + c8 * 2);
;       }
;     } else {
;       const int c8 = (tid & 31) * 8;
;       const f32x4 sg0 = *reinterpret_cast<const f32x4*>(subg + c8), sg1 = *reinterpret_cast<const f32x4*>(subg + c8 + 4);
;       u32x4 a1[8];
; #pragma unroll
;       for (int it = 0; it < 8; ++it) a1[it] = *reinterpret_cast<const u32x4*>(O1 + (long)((tid >> 5) + 16 * it) * DM + c8);
; #pragma unroll
;       for (int it = 0; it < 8; ++it) {
;         const int row = (tid >> 5) + 16 * it;
;         const u32x4 a2 = *reinterpret_cast<const u32x4*>(Ot + row * UOROW + c8 * 2);
;         f32x4 v0 = bf4lo(a1[it]) - bf4lo(a2) * lam, v1 = bf4hi(a1[it]) - bf4hi(a2) * lam;
;         float ss = 0.f;
; #pragma unroll
;         for (int e = 0; e < 4; ++e) ss = fmaf(v0[e], v0[e], fmaf(v1[e], v1[e], ss));
;         ss += __shfl_xor(ss, 1, 64); ss += __shfl_xor(ss, 2, 64); ss += __shfl_xor(ss, 4, 64); ss += __shfl_xor(ss, 8, 64); ss += __shfl_xor(ss, 16, 64);
	ds_write_b16 v72, v0 offset:9568
	v_mul_f32_e32 v0, v42, v66
	v_cvt_pk_bf16_f32 v0, v0, v0
	ds_write_b16 v72, v0 offset:9632
	v_mul_f32_e32 v0, v58, v66
	v_cvt_pk_bf16_f32 v0, v0, v0
	ds_write_b16 v72, v0 offset:9696
	v_mul_f32_e32 v0, v11, v67
	v_cvt_pk_bf16_f32 v0, v0, v0
	ds_write_b16 v72, v0 offset:10032
	v_mul_f32_e32 v0, v27, v67
	v_cvt_pk_bf16_f32 v0, v0, v0
	v_rcp_f32_e32 v70, v70
	ds_write_b16 v72, v0 offset:10096
	v_mul_f32_e32 v0, v43, v67
	v_cvt_pk_bf16_f32 v0, v0, v0
	ds_write_b16 v72, v0 offset:10160
	v_mul_f32_e32 v0, v59, v67
	v_cvt_pk_bf16_f32 v0, v0, v0
	ds_write_b16 v72, v0 offset:10224
	v_mul_f32_e32 v0, v12, v70
	v_cvt_pk_bf16_f32 v0, v0, v0
	ds_write_b16 v72, v0 offset:12672
	v_mul_f32_e32 v0, v28, v70
	v_cvt_pk_bf16_f32 v0, v0, v0
	v_rcp_f32_e32 v64, v64
	ds_write_b16 v72, v0 offset:12736
	v_mul_f32_e32 v0, v44, v70
	v_cvt_pk_bf16_f32 v0, v0, v0
	ds_write_b16 v72, v0 offset:12800
	v_mul_f32_e32 v0, v60, v70
	v_cvt_pk_bf16_f32 v0, v0, v0
	ds_write_b16 v72, v0 offset:12864
	v_mul_f32_e32 v0, v13, v64
	v_cvt_pk_bf16_f32 v0, v0, v0
	ds_write_b16 v72, v0 offset:13200
	v_mul_f32_e32 v0, v29, v64
	v_cvt_pk_bf16_f32 v0, v0, v0
	v_rcp_f32_e32 v65, v65
	ds_write_b16 v72, v0 offset:13264
	v_mul_f32_e32 v0, v45, v64
	v_cvt_pk_bf16_f32 v0, v0, v0
	ds_write_b16 v72, v0 offset:13328
	v_mul_f32_e32 v0, v61, v64
	v_cvt_pk_bf16_f32 v0, v0, v0
	ds_write_b16 v72, v0 offset:13392
	v_mul_f32_e32 v0, v14, v65
	v_cvt_pk_bf16_f32 v0, v0, v0
	ds_write_b16 v72, v0 offset:13728
	v_mul_f32_e32 v0, v30, v65
	s_waitcnt lgkmcnt(14)
	v_add_f32_e32 v71, v87, v71
	v_cvt_pk_bf16_f32 v0, v0, v0
	v_rcp_f32_e32 v71, v71
	ds_write_b16 v72, v0 offset:13792
	v_mul_f32_e32 v0, v46, v65
	v_cvt_pk_bf16_f32 v0, v0, v0
	ds_write_b16 v72, v0 offset:13856
	v_mul_f32_e32 v0, v62, v65
	v_cvt_pk_bf16_f32 v0, v0, v0
	ds_write_b16 v72, v0 offset:13920
	v_mul_f32_e32 v0, v15, v71
	v_cvt_pk_bf16_f32 v0, v0, v0
	ds_write_b16 v72, v0 offset:14256
	v_mul_f32_e32 v0, v31, v71
	v_cvt_pk_bf16_f32 v0, v0, v0
	ds_write_b16 v72, v0 offset:14320
	v_mul_f32_e32 v0, v47, v71
	v_cvt_pk_bf16_f32 v0, v0, v0
	v_and_b32_e32 v2, 0xf8, v86
	v_ashrrev_i32_e32 v12, 5, v175
	ds_write_b16 v72, v0 offset:14384
	v_mul_f32_e32 v0, v63, v71
	v_lshlrev_b32_e32 v176, 1, v2
	v_ashrrev_i32_e32 v13, 31, v12
	v_cvt_pk_bf16_f32 v0, v0, v0
	v_lshl_add_u64 v[34:35], s[48:49], 0, v[176:177]
	v_lshlrev_b64 v[46:47], 12, v[12:13]
	ds_write_b16 v72, v0 offset:14448
	v_lshl_add_u64 v[0:1], v[34:35], 0, v[46:47]
	s_waitcnt lgkmcnt(0)
	s_barrier
	global_load_dwordx4 v[8:11], v[0:1], off
	v_readlane_b32 s16, v250, 12
	v_lshlrev_b32_e32 v0, 2, v2
	v_readlane_b32 s30, v250, 26
	v_readlane_b32 s31, v250, 27
	s_nop 4
	global_load_dwordx4 v[4:7], v0, s[30:31]
	s_nop 0
	global_load_dwordx4 v[0:3], v0, s[30:31] offset:16
	v_lshl_add_u64 v[44:45], v[46:47], 0, s[0:1]
	v_lshl_add_u64 v[14:15], v[34:35], 0, v[44:45]
	global_load_dwordx4 v[50:53], v[14:15], off
	v_readlane_b32 s28, v250, 24
	s_movk_i32 s28, 0x210
	v_xor_b32_e32 v29, 0x80000000, v81
	v_mul_lo_u32 v12, v12, s28
	v_add3_u32 v48, 16, v176, v12
	ds_read_b128 v[12:15], v48
	v_xor_b32_e32 v28, 0x80000000, v80
	s_mov_b64 s[30:31], 0x20000
	v_lshl_add_u64 v[42:43], v[46:47], 0, s[30:31]
	s_mov_b64 s[0:1], 0x30000
	s_waitcnt lgkmcnt(0)
	v_lshlrev_b32_e32 v18, 16, v12
	v_and_b32_e32 v19, 0xffff0000, v12
	v_lshlrev_b32_e32 v12, 16, v13
	v_and_b32_e32 v13, 0xffff0000, v13
	v_lshl_add_u64 v[40:41], v[46:47], 0, s[0:1]
	s_mov_b64 s[0:1], 0x40000
	v_lshl_add_u64 v[38:39], v[46:47], 0, s[0:1]
	s_mov_b64 s[0:1], 0x50000
	v_lshl_add_u64 v[36:37], v[46:47], 0, s[0:1]
	s_mov_b64 s[0:1], 0x60000
	v_lshl_add_u64 v[32:33], v[46:47], 0, s[0:1]
	s_mov_b64 s[0:1], 0x70000
	v_lshl_add_u64 v[30:31], v[46:47], 0, s[0:1]
	s_add_u32 s0, s50, s46
	s_addc_u32 s1, s51, s47
	s_add_u32 s0, s0, s74
	s_addc_u32 s1, s1, 0
	s_add_i32 s2, s2, s94
	s_cmpk_gt_i32 s2, 0x3ff
	v_readlane_b32 s17, v250, 13
	v_readlane_b32 s18, v250, 14
	v_readlane_b32 s19, v250, 15
	v_readlane_b32 s20, v250, 16
	v_readlane_b32 s21, v250, 17
	v_readlane_b32 s22, v250, 18
	v_readlane_b32 s23, v250, 19
	v_readlane_b32 s24, v250, 20
	v_readlane_b32 s25, v250, 21
	v_readlane_b32 s26, v250, 22
	v_readlane_b32 s27, v250, 23
	v_readlane_b32 s29, v250, 25
	s_waitcnt vmcnt(3)
	v_lshlrev_b32_e32 v16, 16, v8
	v_and_b32_e32 v17, 0xffff0000, v8
	v_lshlrev_b32_e32 v8, 16, v9
	v_and_b32_e32 v9, 0xffff0000, v9
	v_pk_fma_f32 v[58:59], v[28:29], v[12:13], v[8:9]
	v_lshlrev_b32_e32 v8, 16, v10
	v_and_b32_e32 v9, 0xffff0000, v10
	v_lshlrev_b32_e32 v12, 16, v14
	v_and_b32_e32 v13, 0xffff0000, v14
	v_pk_fma_f32 v[64:65], v[150:151], v[12:13], v[8:9] neg_lo:[1,0,0] neg_hi:[1,0,0]
	v_pk_fma_f32 v[60:61], v[150:151], v[18:19], v[16:17] neg_lo:[1,0,0] neg_hi:[1,0,0]
	v_fma_f32 v8, v64, v64, 0
	v_fmac_f32_e32 v8, v60, v60
	v_lshlrev_b32_e32 v10, 16, v11
	v_and_b32_e32 v11, 0xffff0000, v11
	v_lshlrev_b32_e32 v14, 16, v15
	v_and_b32_e32 v15, 0xffff0000, v15
	v_fmac_f32_e32 v8, v65, v65
	v_pk_fma_f32 v[62:63], v[28:29], v[14:15], v[10:11]
	v_fmac_f32_e32 v8, v61, v61
	v_fmac_f32_e32 v8, v62, v62
	v_fmac_f32_e32 v8, v58, v58
	v_fmac_f32_e32 v8, v63, v63
	v_fmac_f32_e32 v8, v59, v59
	s_waitcnt vmcnt(2)
	v_pk_mul_f32 v[60:61], v[4:5], v[60:61]
	v_pk_mul_f32 v[58:59], v[6:7], v[58:59]
	s_waitcnt vmcnt(1)
	v_pk_mul_f32 v[62:63], v[2:3], v[62:63]
	s_waitcnt lgkmcnt(0)
	s_nop 1
	v_add_f32_dpp v10, v8, v8 quad_perm:[1,0,3,2] row_mask:0xf bank_mask:0xf
	v_lshl_add_u64 v[8:9], v[34:35], 0, v[42:43]
	s_waitcnt lgkmcnt(0)
; DI u32x4 pack8(f32x4 a, f32x4 b) { u32x4 w = {cvtpk(a[0], a[1]), cvtpk(a[2], a[3]), cvtpk(b[0], b[1]), cvtpk(b[2], b[3])}; return w; }
; DI f32x4 bf4lo(u32x4 w) { f32x4 r = {bflo(w[0]), bfhi(w[0]), bflo(w[1]), bfhi(w[1])}; return r; }
; DI f32x4 bf4hi(u32x4 w) { f32x4 r = {bflo(w[2]), bfhi(w[2]), bflo(w[3]), bfhi(w[3])}; return r; }
; template <int PROBE, int MODE>
; DI void dattn_body(const u16* __restrict__ Qb, const u16* __restrict__ Kh, const u16* __restrict__ Vh, u16* __restrict__ Ob, const u16* __restrict__ O1, float lam, const float* __restrict__ subg, int seq, int q0, float kmax2, char* lds) {
;     ...
;       for (int it = 0; it < 8; ++it) a1[it] = *reinterpret_cast<const u32x4*>(O1 + (long)((tid >> 5) + 16 * it) * DM + c8);
; #pragma unroll
;       for (int it = 0; it < 8; ++it) {
;         const int row = (tid >> 5) + 16 * it;
;         const u32x4 a2 = *reinterpret_cast<const u32x4*>(Ot + row * UOROW + c8 * 2);
;         f32x4 v0 = bf4lo(a1[it]) - bf4lo(a2) * lam, v1 = bf4hi(a1[it]) - bf4hi(a2) * lam;
;         float ss = 0.f;
; #pragma unroll
;         for (int e = 0; e < 4; ++e) ss = fmaf(v0[e], v0[e], fmaf(v1[e], v1[e], ss));
;         ss += __shfl_xor(ss, 1, 64); ss += __shfl_xor(ss, 2, 64); ss += __shfl_xor(ss, 4, 64); ss += __shfl_xor(ss, 8, 64); ss += __shfl_xor(ss, 16, 64);
;         const float sc = rsqrtf(ss * (1.f / 256.f) + 1e-5f) * 0.8f;
;         *reinterpret_cast<u32x4*>(Ob + (long)row * DM + c8) = pack8(v0 * sg0 * sc, v1 * sg1 * sc);
;       }
	s_nop 1
	v_add_f32_dpp v12, v10, v10 quad_perm:[2,3,0,1] row_mask:0xf bank_mask:0xf
	v_lshl_add_u64 v[10:11], v[34:35], 0, v[40:41]
	global_load_dwordx4 v[54:57], v[8:9], off
	global_load_dwordx4 v[24:27], v[10:11], off
	v_lshl_add_u64 v[8:9], v[34:35], 0, v[38:39]
	v_lshl_add_u64 v[10:11], v[34:35], 0, v[36:37]
	s_waitcnt lgkmcnt(0)
	s_nop 1
	v_add_f32_dpp v12, v12, v12 row_half_mirror row_mask:0xf bank_mask:0xf
	global_load_dwordx4 v[20:23], v[8:9], off
	global_load_dwordx4 v[16:19], v[10:11], off
	v_lshl_add_u64 v[8:9], v[34:35], 0, v[32:33]
	s_waitcnt lgkmcnt(0)
	s_nop 1
	v_add_f32_dpp v12, v12, v12 row_mirror row_mask:0xf bank_mask:0xf
	ds_bpermute_b32 v13, v161, v12
	s_waitcnt lgkmcnt(0)
	v_add_f32_e32 v10, v12, v13
	v_fmamk_f32 v10, v10, 0x3b800000, v218
	v_mul_f32_e32 v11, 0x4b800000, v10
	v_cmp_gt_f32_e32 vcc, s78, v10
	s_nop 1
	v_cndmask_b32_e32 v10, v10, v11, vcc
	v_rsq_f32_e32 v49, v10
	v_lshl_add_u64 v[10:11], v[34:35], 0, v[30:31]
	global_load_dwordx4 v[12:15], v[8:9], off
	s_nop 0
	global_load_dwordx4 v[8:11], v[10:11], off
	v_mul_f32_e32 v34, 0x45800000, v49
	v_cndmask_b32_e32 v34, v49, v34, vcc
	v_mul_f32_e32 v34, 0x3f4ccccd, v34
	v_pk_mul_f32 v[66:67], v[58:59], v[34:35] op_sel_hi:[1,0]
	v_pk_mul_f32 v[58:59], v[60:61], v[34:35] op_sel_hi:[1,0]
	v_pk_mul_f32 v[60:61], v[0:1], v[64:65]
	v_pk_mul_f32 v[62:63], v[62:63], v[34:35] op_sel_hi:[1,0]
	v_pk_mul_f32 v[34:35], v[60:61], v[34:35] op_sel_hi:[1,0]
	v_cvt_pk_bf16_f32 v58, v58, v59
	v_cvt_pk_bf16_f32 v59, v66, v67
	s_nop 0
	v_cvt_pk_bf16_f32 v60, v34, v35
	v_cvt_pk_bf16_f32 v61, v62, v63
	ds_read_b128 v[62:65], v48 offset:8448
	s_waitcnt vmcnt(6)
	v_lshlrev_b32_e32 v34, 16, v50
	v_and_b32_e32 v35, 0xffff0000, v50
	v_lshlrev_b32_e32 v50, 16, v51
	v_and_b32_e32 v51, 0xffff0000, v51
	s_waitcnt lgkmcnt(0)
	v_lshlrev_b32_e32 v66, 16, v62
	v_and_b32_e32 v67, 0xffff0000, v62
	v_lshlrev_b32_e32 v62, 16, v63
	v_and_b32_e32 v63, 0xffff0000, v63
	v_pk_fma_f32 v[50:51], v[28:29], v[62:63], v[50:51]
	v_pk_fma_f32 v[62:63], v[150:151], v[66:67], v[34:35] neg_lo:[1,0,0] neg_hi:[1,0,0]
	v_lshlrev_b32_e32 v34, 16, v52
	v_and_b32_e32 v35, 0xffff0000, v52
	v_lshlrev_b32_e32 v52, 16, v53
	v_and_b32_e32 v53, 0xffff0000, v53
	v_lshlrev_b32_e32 v66, 16, v64
	v_and_b32_e32 v67, 0xffff0000, v64
	v_lshlrev_b32_e32 v64, 16, v65
	v_and_b32_e32 v65, 0xffff0000, v65
	v_pk_fma_f32 v[52:53], v[28:29], v[64:65], v[52:53]
	v_pk_fma_f32 v[64:65], v[150:151], v[66:67], v[34:35] neg_lo:[1,0,0] neg_hi:[1,0,0]
	s_nop 0
	v_fma_f32 v34, v64, v64, 0
	v_fmac_f32_e32 v34, v62, v62
	v_fmac_f32_e32 v34, v65, v65
	v_fmac_f32_e32 v34, v63, v63
	v_fmac_f32_e32 v34, v52, v52
	v_fmac_f32_e32 v34, v50, v50
	v_fmac_f32_e32 v34, v53, v53
	v_fmac_f32_e32 v34, v51, v51
	v_pk_mul_f32 v[50:51], v[6:7], v[50:51]
	v_pk_mul_f32 v[52:53], v[2:3], v[52:53]
	s_waitcnt lgkmcnt(0)
	s_nop 1
	v_add_f32_dpp v34, v34, v34 quad_perm:[1,0,3,2] row_mask:0xf bank_mask:0xf
	s_waitcnt lgkmcnt(0)
	s_nop 1
	v_add_f32_dpp v34, v34, v34 quad_perm:[2,3,0,1] row_mask:0xf bank_mask:0xf
	s_waitcnt lgkmcnt(0)
	s_nop 1
	v_add_f32_dpp v34, v34, v34 row_half_mirror row_mask:0xf bank_mask:0xf
	s_waitcnt lgkmcnt(0)
	s_nop 1
	v_add_f32_dpp v34, v34, v34 row_mirror row_mask:0xf bank_mask:0xf
	ds_bpermute_b32 v35, v161, v34
	s_waitcnt lgkmcnt(0)
	v_add_f32_e32 v34, v34, v35
	v_fmamk_f32 v34, v34, 0x3b800000, v218
	v_mul_f32_e32 v35, 0x4b800000, v34
	v_cmp_gt_f32_e32 vcc, s78, v34
	s_nop 1
	v_cndmask_b32_e32 v34, v34, v35, vcc
	v_rsq_f32_e32 v49, v34
	v_lshl_add_u64 v[34:35], s[0:1], 0, v[176:177]
	v_lshl_add_u64 v[46:47], v[34:35], 0, v[46:47]
	global_store_dwordx4 v[46:47], v[58:61], off
	v_mul_f32_e32 v46, 0x45800000, v49
	v_cndmask_b32_e32 v46, v49, v46, vcc
	v_mul_f32_e32 v46, 0x3f4ccccd, v46
	v_pk_mul_f32 v[58:59], v[4:5], v[62:63]
	v_pk_mul_f32 v[60:61], v[50:51], v[46:47] op_sel_hi:[1,0]
	v_pk_mul_f32 v[50:51], v[58:59], v[46:47] op_sel_hi:[1,0]
	v_pk_mul_f32 v[58:59], v[0:1], v[64:65]
	v_pk_mul_f32 v[62:63], v[52:53], v[46:47] op_sel_hi:[1,0]
	v_pk_mul_f32 v[46:47], v[58:59], v[46:47] op_sel_hi:[1,0]
	v_cvt_pk_bf16_f32 v50, v50, v51
	v_cvt_pk_bf16_f32 v51, v60, v61
	v_lshl_add_u64 v[44:45], v[34:35], 0, v[44:45]
	v_cvt_pk_bf16_f32 v52, v46, v47
	v_cvt_pk_bf16_f32 v53, v62, v63
	ds_read_b128 v[58:61], v48 offset:16896
	s_waitcnt vmcnt(6)
	v_lshlrev_b32_e32 v46, 16, v54
	v_and_b32_e32 v47, 0xffff0000, v54
	v_lshlrev_b32_e32 v54, 16, v55
	v_and_b32_e32 v55, 0xffff0000, v55
	s_waitcnt lgkmcnt(0)
	v_lshlrev_b32_e32 v62, 16, v58
	v_and_b32_e32 v63, 0xffff0000, v58
	v_lshlrev_b32_e32 v58, 16, v59
	v_and_b32_e32 v59, 0xffff0000, v59
	v_pk_fma_f32 v[54:55], v[28:29], v[58:59], v[54:55]
	v_pk_fma_f32 v[46:47], v[150:151], v[62:63], v[46:47] neg_lo:[1,0,0] neg_hi:[1,0,0]
	v_lshlrev_b32_e32 v58, 16, v56
	v_and_b32_e32 v59, 0xffff0000, v56
	v_lshlrev_b32_e32 v62, 16, v60
	v_and_b32_e32 v63, 0xffff0000, v60
	v_pk_fma_f32 v[58:59], v[150:151], v[62:63], v[58:59] neg_lo:[1,0,0] neg_hi:[1,0,0]
	v_lshlrev_b32_e32 v56, 16, v57
	v_fma_f32 v49, v58, v58, 0
	v_fmac_f32_e32 v49, v46, v46
	v_and_b32_e32 v57, 0xffff0000, v57
	v_lshlrev_b32_e32 v60, 16, v61
	v_and_b32_e32 v61, 0xffff0000, v61
	v_fmac_f32_e32 v49, v59, v59
	v_pk_fma_f32 v[56:57], v[28:29], v[60:61], v[56:57]
	v_fmac_f32_e32 v49, v47, v47
	v_fmac_f32_e32 v49, v56, v56
	v_fmac_f32_e32 v49, v54, v54
	v_fmac_f32_e32 v49, v57, v57
	v_fmac_f32_e32 v49, v55, v55
	global_store_dwordx4 v[44:45], v[50:53], off
	v_pk_mul_f32 v[46:47], v[4:5], v[46:47]
	v_lshl_add_u64 v[42:43], v[34:35], 0, v[42:43]
	v_pk_mul_f32 v[50:51], v[6:7], v[54:55]
	s_waitcnt lgkmcnt(0)
; DI u32x4 pack8(f32x4 a, f32x4 b) { u32x4 w = {cvtpk(a[0], a[1]), cvtpk(a[2], a[3]), cvtpk(b[0], b[1]), cvtpk(b[2], b[3])}; return w; }
; DI f32x4 bf4lo(u32x4 w) { f32x4 r = {bflo(w[0]), bfhi(w[0]), bflo(w[1]), bfhi(w[1])}; return r; }
; DI f32x4 bf4hi(u32x4 w) { f32x4 r = {bflo(w[2]), bfhi(w[2]), bflo(w[3]), bfhi(w[3])}; return r; }
; template <int PROBE, int MODE>
; DI void dattn_body(const u16* __restrict__ Qb, const u16* __restrict__ Kh, const u16* __restrict__ Vh, u16* __restrict__ Ob, const u16* __restrict__ O1, float lam, const float* __restrict__ subg, int seq, int q0, float kmax2, char* lds) {
;     ...
;       for (int it = 0; it < 8; ++it) {
;         const int row = (tid >> 5) + 16 * it;
;         const u32x4 a2 = *reinterpret_cast<const u32x4*>(Ot + row * UOROW + c8 * 2);
;         f32x4 v0 = bf4lo(a1[it]) - bf4lo(a2) * lam, v1 = bf4hi(a1[it]) - bf4hi(a2) * lam;
;         float ss = 0.f;
; #pragma unroll
;         for (int e = 0; e < 4; ++e) ss = fmaf(v0[e], v0[e], fmaf(v1[e], v1[e], ss));
;         ss += __shfl_xor(ss, 1, 64); ss += __shfl_xor(ss, 2, 64); ss += __shfl_xor(ss, 4, 64); ss += __shfl_xor(ss, 8, 64); ss += __shfl_xor(ss, 16, 64);
;         const float sc = rsqrtf(ss * (1.f / 256.f) + 1e-5f) * 0.8f;
;         *reinterpret_cast<u32x4*>(Ob + (long)row * DM + c8) = pack8(v0 * sg0 * sc, v1 * sg1 * sc);
;       }
	s_nop 1
	v_add_f32_dpp v49, v49, v49 quad_perm:[1,0,3,2] row_mask:0xf bank_mask:0xf
	v_pk_mul_f32 v[52:53], v[0:1], v[58:59]
	v_pk_mul_f32 v[54:55], v[2:3], v[56:57]
	v_lshl_add_u64 v[40:41], v[34:35], 0, v[40:41]
	v_lshl_add_u64 v[38:39], v[34:35], 0, v[38:39]
	s_waitcnt lgkmcnt(0)
	s_nop 1
	v_add_f32_dpp v49, v49, v49 quad_perm:[2,3,0,1] row_mask:0xf bank_mask:0xf
	s_waitcnt lgkmcnt(0)
	s_nop 1
	v_add_f32_dpp v49, v49, v49 row_half_mirror row_mask:0xf bank_mask:0xf
	s_waitcnt lgkmcnt(0)
	s_nop 1
	v_add_f32_dpp v49, v49, v49 row_mirror row_mask:0xf bank_mask:0xf
	ds_bpermute_b32 v60, v161, v49
	s_waitcnt lgkmcnt(0)
	v_add_f32_e32 v49, v49, v60
	v_fmamk_f32 v49, v49, 0x3b800000, v218
	v_mul_f32_e32 v60, 0x4b800000, v49
	v_cmp_gt_f32_e32 vcc, s78, v49
	s_nop 1
	v_cndmask_b32_e32 v49, v49, v60, vcc
	v_rsq_f32_e32 v49, v49
	s_nop 0
	v_mul_f32_e32 v44, 0x45800000, v49
	v_cndmask_b32_e32 v44, v49, v44, vcc
	v_mul_f32_e32 v44, 0x3f4ccccd, v44
	v_pk_mul_f32 v[50:51], v[50:51], v[44:45] op_sel_hi:[1,0]
	v_pk_mul_f32 v[46:47], v[46:47], v[44:45] op_sel_hi:[1,0]
	v_pk_mul_f32 v[52:53], v[52:53], v[44:45] op_sel_hi:[1,0]
	v_pk_mul_f32 v[54:55], v[54:55], v[44:45] op_sel_hi:[1,0]
	v_cvt_pk_bf16_f32 v44, v46, v47
	v_cvt_pk_bf16_f32 v45, v50, v51
	v_cvt_pk_bf16_f32 v46, v52, v53
	s_nop 0
	v_cvt_pk_bf16_f32 v47, v54, v55
	ds_read_b128 v[50:53], v48 offset:25344
	s_waitcnt vmcnt(6)
	v_lshlrev_b32_e32 v54, 16, v24
	v_and_b32_e32 v55, 0xffff0000, v24
	v_lshlrev_b32_e32 v24, 16, v25
	v_and_b32_e32 v25, 0xffff0000, v25
	s_waitcnt lgkmcnt(0)
	v_lshlrev_b32_e32 v56, 16, v50
	v_and_b32_e32 v57, 0xffff0000, v50
	v_lshlrev_b32_e32 v50, 16, v51
	v_and_b32_e32 v51, 0xffff0000, v51
	v_pk_fma_f32 v[24:25], v[28:29], v[50:51], v[24:25]
	v_pk_fma_f32 v[50:51], v[150:151], v[56:57], v[54:55] neg_lo:[1,0,0] neg_hi:[1,0,0]
	v_lshlrev_b32_e32 v54, 16, v26
	v_and_b32_e32 v55, 0xffff0000, v26
	v_lshlrev_b32_e32 v26, 16, v27
	v_and_b32_e32 v27, 0xffff0000, v27
	v_lshlrev_b32_e32 v56, 16, v52
	v_and_b32_e32 v57, 0xffff0000, v52
	v_lshlrev_b32_e32 v52, 16, v53
	v_and_b32_e32 v53, 0xffff0000, v53
	v_pk_fma_f32 v[26:27], v[28:29], v[52:53], v[26:27]
	v_pk_fma_f32 v[52:53], v[150:151], v[56:57], v[54:55] neg_lo:[1,0,0] neg_hi:[1,0,0]
	global_store_dwordx4 v[42:43], v[44:47], off
	v_fma_f32 v49, v52, v52, 0
	v_fmac_f32_e32 v49, v50, v50
	v_fmac_f32_e32 v49, v53, v53
	v_fmac_f32_e32 v49, v51, v51
	v_fmac_f32_e32 v49, v26, v26
	v_fmac_f32_e32 v49, v24, v24
	v_fmac_f32_e32 v49, v27, v27
	v_fmac_f32_e32 v49, v25, v25
	v_pk_mul_f32 v[44:45], v[4:5], v[50:51]
	v_pk_mul_f32 v[24:25], v[6:7], v[24:25]
	v_pk_mul_f32 v[26:27], v[2:3], v[26:27]
	s_waitcnt lgkmcnt(0)
	s_nop 1
	v_add_f32_dpp v49, v49, v49 quad_perm:[1,0,3,2] row_mask:0xf bank_mask:0xf
	s_waitcnt lgkmcnt(0)
	s_nop 1
	v_add_f32_dpp v49, v49, v49 quad_perm:[2,3,0,1] row_mask:0xf bank_mask:0xf
	s_waitcnt lgkmcnt(0)
	s_nop 1
	v_add_f32_dpp v49, v49, v49 row_half_mirror row_mask:0xf bank_mask:0xf
	s_waitcnt lgkmcnt(0)
	s_nop 1
	v_add_f32_dpp v49, v49, v49 row_mirror row_mask:0xf bank_mask:0xf
	ds_bpermute_b32 v54, v161, v49
	s_waitcnt lgkmcnt(0)
	v_add_f32_e32 v49, v49, v54
	v_fmamk_f32 v49, v49, 0x3b800000, v218
	v_mul_f32_e32 v54, 0x4b800000, v49
	v_cmp_gt_f32_e32 vcc, s78, v49
	s_nop 1
	v_cndmask_b32_e32 v49, v49, v54, vcc
	v_rsq_f32_e32 v49, v49
	s_nop 0
	v_mul_f32_e32 v42, 0x45800000, v49
	v_cndmask_b32_e32 v42, v49, v42, vcc
	v_mul_f32_e32 v42, 0x3f4ccccd, v42
	v_pk_mul_f32 v[46:47], v[24:25], v[42:43] op_sel_hi:[1,0]
	v_pk_mul_f32 v[24:25], v[44:45], v[42:43] op_sel_hi:[1,0]
	v_pk_mul_f32 v[44:45], v[0:1], v[52:53]
	v_pk_mul_f32 v[50:51], v[26:27], v[42:43] op_sel_hi:[1,0]
	v_pk_mul_f32 v[26:27], v[44:45], v[42:43] op_sel_hi:[1,0]
	v_cvt_pk_bf16_f32 v24, v24, v25
	v_cvt_pk_bf16_f32 v25, v46, v47
	s_waitcnt vmcnt(6)
	v_lshlrev_b32_e32 v46, 16, v20
	v_cvt_pk_bf16_f32 v26, v26, v27
	v_cvt_pk_bf16_f32 v27, v50, v51
	ds_read_b128 v[42:45], v48 offset:33792
	v_and_b32_e32 v47, 0xffff0000, v20
	v_lshlrev_b32_e32 v20, 16, v21
	v_and_b32_e32 v21, 0xffff0000, v21
	global_store_dwordx4 v[40:41], v[24:27], off
	s_waitcnt lgkmcnt(0)
	v_lshlrev_b32_e32 v50, 16, v42
	v_and_b32_e32 v51, 0xffff0000, v42
	v_lshlrev_b32_e32 v42, 16, v43
	v_and_b32_e32 v43, 0xffff0000, v43
	v_pk_fma_f32 v[20:21], v[28:29], v[42:43], v[20:21]
	v_pk_fma_f32 v[42:43], v[150:151], v[50:51], v[46:47] neg_lo:[1,0,0] neg_hi:[1,0,0]
	v_lshlrev_b32_e32 v46, 16, v22
	v_and_b32_e32 v47, 0xffff0000, v22
	v_lshlrev_b32_e32 v22, 16, v23
	v_and_b32_e32 v23, 0xffff0000, v23
	v_lshlrev_b32_e32 v50, 16, v44
	v_and_b32_e32 v51, 0xffff0000, v44
	v_lshlrev_b32_e32 v44, 16, v45
	v_and_b32_e32 v45, 0xffff0000, v45
	v_pk_fma_f32 v[22:23], v[28:29], v[44:45], v[22:23]
	v_pk_fma_f32 v[44:45], v[150:151], v[50:51], v[46:47] neg_lo:[1,0,0] neg_hi:[1,0,0]
	v_pk_mul_f32 v[26:27], v[4:5], v[42:43]
	v_fma_f32 v46, v44, v44, 0
	v_fmac_f32_e32 v46, v42, v42
	v_fmac_f32_e32 v46, v45, v45
	v_fmac_f32_e32 v46, v43, v43
	v_fmac_f32_e32 v46, v22, v22
	v_fmac_f32_e32 v46, v20, v20
	v_fmac_f32_e32 v46, v23, v23
	v_fmac_f32_e32 v46, v21, v21
	v_pk_mul_f32 v[20:21], v[6:7], v[20:21]
	v_pk_mul_f32 v[22:23], v[2:3], v[22:23]
	s_waitcnt lgkmcnt(0)
	s_nop 1
	v_add_f32_dpp v46, v46, v46 quad_perm:[1,0,3,2] row_mask:0xf bank_mask:0xf
	s_waitcnt lgkmcnt(0)
	s_nop 1
	v_add_f32_dpp v46, v46, v46 quad_perm:[2,3,0,1] row_mask:0xf bank_mask:0xf
	s_waitcnt lgkmcnt(0)
	s_nop 1
	v_add_f32_dpp v46, v46, v46 row_half_mirror row_mask:0xf bank_mask:0xf
	s_waitcnt lgkmcnt(0)
	s_nop 1
	v_add_f32_dpp v46, v46, v46 row_mirror row_mask:0xf bank_mask:0xf
	ds_bpermute_b32 v47, v161, v46
	s_waitcnt lgkmcnt(0)
; DI u32x4 pack8(f32x4 a, f32x4 b) { u32x4 w = {cvtpk(a[0], a[1]), cvtpk(a[2], a[3]), cvtpk(b[0], b[1]), cvtpk(b[2], b[3])}; return w; }
; DI f32x4 bf4lo(u32x4 w) { f32x4 r = {bflo(w[0]), bfhi(w[0]), bflo(w[1]), bfhi(w[1])}; return r; }
; DI f32x4 bf4hi(u32x4 w) { f32x4 r = {bflo(w[2]), bfhi(w[2]), bflo(w[3]), bfhi(w[3])}; return r; }
; template <int PROBE, int MODE>
; DI void dattn_body(const u16* __restrict__ Qb, const u16* __restrict__ Kh, const u16* __restrict__ Vh, u16* __restrict__ Ob, const u16* __restrict__ O1, float lam, const float* __restrict__ subg, int seq, int q0, float kmax2, char* lds) {
;     ...
;       for (int it = 0; it < 8; ++it) {
;         const int row = (tid >> 5) + 16 * it;
;         const u32x4 a2 = *reinterpret_cast<const u32x4*>(Ot + row * UOROW + c8 * 2);
;         f32x4 v0 = bf4lo(a1[it]) - bf4lo(a2) * lam, v1 = bf4hi(a1[it]) - bf4hi(a2) * lam;
;         float ss = 0.f;
; #pragma unroll
;         for (int e = 0; e < 4; ++e) ss = fmaf(v0[e], v0[e], fmaf(v1[e], v1[e], ss));
;         ss += __shfl_xor(ss, 1, 64); ss += __shfl_xor(ss, 2, 64); ss += __shfl_xor(ss, 4, 64); ss += __shfl_xor(ss, 8, 64); ss += __shfl_xor(ss, 16, 64);
;         const float sc = rsqrtf(ss * (1.f / 256.f) + 1e-5f) * 0.8f;
;         *reinterpret_cast<u32x4*>(Ob + (long)row * DM + c8) = pack8(v0 * sg0 * sc, v1 * sg1 * sc);
;       }
	v_add_f32_e32 v46, v46, v47
	v_fmamk_f32 v46, v46, 0x3b800000, v218
	v_mul_f32_e32 v47, 0x4b800000, v46
	v_cmp_gt_f32_e32 vcc, s78, v46
	s_nop 1
	v_cndmask_b32_e32 v46, v46, v47, vcc
	v_rsq_f32_e32 v46, v46
	s_nop 0
	v_mul_f32_e32 v24, 0x45800000, v46
	v_cndmask_b32_e32 v24, v46, v24, vcc
	v_mul_f32_e32 v24, 0x3f4ccccd, v24
	v_pk_mul_f32 v[40:41], v[20:21], v[24:25] op_sel_hi:[1,0]
	v_pk_mul_f32 v[20:21], v[26:27], v[24:25] op_sel_hi:[1,0]
	v_pk_mul_f32 v[26:27], v[0:1], v[44:45]
	v_pk_mul_f32 v[42:43], v[22:23], v[24:25] op_sel_hi:[1,0]
	v_pk_mul_f32 v[22:23], v[26:27], v[24:25] op_sel_hi:[1,0]
	v_cvt_pk_bf16_f32 v20, v20, v21
	v_cvt_pk_bf16_f32 v21, v40, v41
	s_waitcnt vmcnt(6)
	v_lshlrev_b32_e32 v40, 16, v16
	v_cvt_pk_bf16_f32 v22, v22, v23
	v_cvt_pk_bf16_f32 v23, v42, v43
	ds_read_b128 v[24:27], v48 offset:42240
	v_and_b32_e32 v41, 0xffff0000, v16
	v_lshlrev_b32_e32 v16, 16, v17
	v_and_b32_e32 v17, 0xffff0000, v17
	global_store_dwordx4 v[38:39], v[20:23], off
	s_waitcnt lgkmcnt(0)
	v_lshlrev_b32_e32 v42, 16, v24
	v_and_b32_e32 v43, 0xffff0000, v24
	v_lshlrev_b32_e32 v24, 16, v25
	v_and_b32_e32 v25, 0xffff0000, v25
	v_pk_fma_f32 v[16:17], v[28:29], v[24:25], v[16:17]
	v_pk_fma_f32 v[24:25], v[150:151], v[42:43], v[40:41] neg_lo:[1,0,0] neg_hi:[1,0,0]
	v_lshlrev_b32_e32 v40, 16, v18
	v_and_b32_e32 v41, 0xffff0000, v18
	v_lshlrev_b32_e32 v18, 16, v19
	v_and_b32_e32 v19, 0xffff0000, v19
	v_lshlrev_b32_e32 v42, 16, v26
	v_and_b32_e32 v43, 0xffff0000, v26
	v_lshlrev_b32_e32 v26, 16, v27
	v_and_b32_e32 v27, 0xffff0000, v27
	v_pk_fma_f32 v[18:19], v[28:29], v[26:27], v[18:19]
	v_pk_fma_f32 v[26:27], v[150:151], v[42:43], v[40:41] neg_lo:[1,0,0] neg_hi:[1,0,0]
	v_pk_mul_f32 v[22:23], v[4:5], v[24:25]
	v_fma_f32 v40, v26, v26, 0
	v_fmac_f32_e32 v40, v24, v24
	v_fmac_f32_e32 v40, v27, v27
	v_fmac_f32_e32 v40, v25, v25
	v_fmac_f32_e32 v40, v18, v18
	v_fmac_f32_e32 v40, v16, v16
	v_fmac_f32_e32 v40, v19, v19
	v_fmac_f32_e32 v40, v17, v17
	v_pk_mul_f32 v[16:17], v[6:7], v[16:17]
	v_pk_mul_f32 v[18:19], v[2:3], v[18:19]
	s_waitcnt lgkmcnt(0)
	s_nop 1
	v_add_f32_dpp v40, v40, v40 quad_perm:[1,0,3,2] row_mask:0xf bank_mask:0xf
	s_waitcnt lgkmcnt(0)
	s_nop 1
	v_add_f32_dpp v40, v40, v40 quad_perm:[2,3,0,1] row_mask:0xf bank_mask:0xf
	s_waitcnt lgkmcnt(0)
	s_nop 1
	v_add_f32_dpp v40, v40, v40 row_half_mirror row_mask:0xf bank_mask:0xf
	s_waitcnt lgkmcnt(0)
	s_nop 1
	v_add_f32_dpp v40, v40, v40 row_mirror row_mask:0xf bank_mask:0xf
	ds_bpermute_b32 v41, v161, v40
	s_waitcnt lgkmcnt(0)
	v_add_f32_e32 v40, v40, v41
	v_fmamk_f32 v40, v40, 0x3b800000, v218
	v_mul_f32_e32 v41, 0x4b800000, v40
	v_cmp_gt_f32_e32 vcc, s78, v40
	s_nop 1
	v_cndmask_b32_e32 v40, v40, v41, vcc
	v_rsq_f32_e32 v40, v40
	s_nop 0
	v_mul_f32_e32 v20, 0x45800000, v40
	v_cndmask_b32_e32 v20, v40, v20, vcc
	v_mul_f32_e32 v20, 0x3f4ccccd, v20
	v_pk_mul_f32 v[24:25], v[16:17], v[20:21] op_sel_hi:[1,0]
	v_pk_mul_f32 v[16:17], v[22:23], v[20:21] op_sel_hi:[1,0]
	v_pk_mul_f32 v[22:23], v[0:1], v[26:27]
	v_pk_mul_f32 v[26:27], v[18:19], v[20:21] op_sel_hi:[1,0]
	v_pk_mul_f32 v[18:19], v[22:23], v[20:21] op_sel_hi:[1,0]
	v_cvt_pk_bf16_f32 v16, v16, v17
	v_cvt_pk_bf16_f32 v17, v24, v25
	s_waitcnt vmcnt(6)
	v_lshlrev_b32_e32 v24, 16, v12
	v_cvt_pk_bf16_f32 v18, v18, v19
	v_cvt_pk_bf16_f32 v19, v26, v27
	ds_read_b128 v[20:23], v48 offset:50688
	v_and_b32_e32 v25, 0xffff0000, v12
	v_lshlrev_b32_e32 v12, 16, v13
	v_and_b32_e32 v13, 0xffff0000, v13
	s_waitcnt lgkmcnt(0)
	v_lshlrev_b32_e32 v26, 16, v20
	v_and_b32_e32 v27, 0xffff0000, v20
	v_lshlrev_b32_e32 v20, 16, v21
	v_and_b32_e32 v21, 0xffff0000, v21
	v_pk_fma_f32 v[12:13], v[28:29], v[20:21], v[12:13]
	v_pk_fma_f32 v[20:21], v[150:151], v[26:27], v[24:25] neg_lo:[1,0,0] neg_hi:[1,0,0]
	v_lshlrev_b32_e32 v24, 16, v14
	v_and_b32_e32 v25, 0xffff0000, v14
	v_lshlrev_b32_e32 v14, 16, v15
	v_and_b32_e32 v15, 0xffff0000, v15
	v_lshlrev_b32_e32 v26, 16, v22
	v_and_b32_e32 v27, 0xffff0000, v22
	v_lshlrev_b32_e32 v22, 16, v23
	v_and_b32_e32 v23, 0xffff0000, v23
	v_pk_fma_f32 v[14:15], v[28:29], v[22:23], v[14:15]
	v_pk_fma_f32 v[22:23], v[150:151], v[26:27], v[24:25] neg_lo:[1,0,0] neg_hi:[1,0,0]
	s_nop 0
	v_fma_f32 v24, v22, v22, 0
	v_fmac_f32_e32 v24, v20, v20
	v_fmac_f32_e32 v24, v23, v23
	v_fmac_f32_e32 v24, v21, v21
	v_fmac_f32_e32 v24, v14, v14
	v_fmac_f32_e32 v24, v12, v12
	v_fmac_f32_e32 v24, v15, v15
	v_fmac_f32_e32 v24, v13, v13
	v_pk_mul_f32 v[12:13], v[6:7], v[12:13]
	v_pk_mul_f32 v[14:15], v[2:3], v[14:15]
	s_waitcnt lgkmcnt(0)
; DI u32x4 pack8(f32x4 a, f32x4 b) { u32x4 w = {cvtpk(a[0], a[1]), cvtpk(a[2], a[3]), cvtpk(b[0], b[1]), cvtpk(b[2], b[3])}; return w; }
; template <int PROBE, int MODE>
; DI void dattn_body(const u16* __restrict__ Qb, const u16* __restrict__ Kh, const u16* __restrict__ Vh, u16* __restrict__ Ob, const u16* __restrict__ O1, float lam, const float* __restrict__ subg, int seq, int q0, float kmax2, char* lds) {
;     ...
;         float ss = 0.f;
; #pragma unroll
;         for (int e = 0; e < 4; ++e) ss = fmaf(v0[e], v0[e], fmaf(v1[e], v1[e], ss));
;         ss += __shfl_xor(ss, 1, 64); ss += __shfl_xor(ss, 2, 64); ss += __shfl_xor(ss, 4, 64); ss += __shfl_xor(ss, 8, 64); ss += __shfl_xor(ss, 16, 64);
;         const float sc = rsqrtf(ss * (1.f / 256.f) + 1e-5f) * 0.8f;
;         *reinterpret_cast<u32x4*>(Ob + (long)row * DM + c8) = pack8(v0 * sg0 * sc, v1 * sg1 * sc);
	s_nop 1
	v_add_f32_dpp v24, v24, v24 quad_perm:[1,0,3,2] row_mask:0xf bank_mask:0xf
	s_waitcnt lgkmcnt(0)
	s_nop 1
	v_add_f32_dpp v24, v24, v24 quad_perm:[2,3,0,1] row_mask:0xf bank_mask:0xf
	s_waitcnt lgkmcnt(0)
	s_nop 1
	v_add_f32_dpp v24, v24, v24 row_half_mirror row_mask:0xf bank_mask:0xf
	s_waitcnt lgkmcnt(0)
	s_nop 1
	v_add_f32_dpp v24, v24, v24 row_mirror row_mask:0xf bank_mask:0xf
	ds_bpermute_b32 v25, v161, v24
	s_waitcnt lgkmcnt(0)
	v_add_f32_e32 v24, v24, v25
	v_fmamk_f32 v24, v24, 0x3b800000, v218
	v_mul_f32_e32 v25, 0x4b800000, v24
	v_cmp_gt_f32_e32 vcc, s78, v24
	s_nop 1
	v_cndmask_b32_e32 v24, v24, v25, vcc
	v_rsq_f32_e32 v26, v24
	v_lshl_add_u64 v[24:25], v[34:35], 0, v[36:37]
	global_store_dwordx4 v[24:25], v[16:19], off
	s_nop 1
	v_mul_f32_e32 v16, 0x45800000, v26
	v_cndmask_b32_e32 v16, v26, v16, vcc
	v_mul_f32_e32 v16, 0x3f4ccccd, v16
	v_pk_mul_f32 v[18:19], v[4:5], v[20:21]
	v_pk_mul_f32 v[20:21], v[12:13], v[16:17] op_sel_hi:[1,0]
	v_pk_mul_f32 v[12:13], v[18:19], v[16:17] op_sel_hi:[1,0]
	v_pk_mul_f32 v[18:19], v[0:1], v[22:23]
	v_pk_mul_f32 v[22:23], v[14:15], v[16:17] op_sel_hi:[1,0]
	v_pk_mul_f32 v[14:15], v[18:19], v[16:17] op_sel_hi:[1,0]
	v_cvt_pk_bf16_f32 v12, v12, v13
	v_cvt_pk_bf16_f32 v13, v20, v21
	s_waitcnt vmcnt(6)
	v_lshlrev_b32_e32 v20, 16, v8
	v_cvt_pk_bf16_f32 v14, v14, v15
	v_cvt_pk_bf16_f32 v15, v22, v23
	ds_read_b128 v[16:19], v48 offset:59136
	v_and_b32_e32 v21, 0xffff0000, v8
	v_lshlrev_b32_e32 v8, 16, v9
	v_and_b32_e32 v9, 0xffff0000, v9
	s_waitcnt lgkmcnt(0)
	v_lshlrev_b32_e32 v22, 16, v16
	v_and_b32_e32 v23, 0xffff0000, v16
	v_lshlrev_b32_e32 v16, 16, v17
	v_and_b32_e32 v17, 0xffff0000, v17
	v_pk_fma_f32 v[8:9], v[28:29], v[16:17], v[8:9]
	v_pk_fma_f32 v[16:17], v[150:151], v[22:23], v[20:21] neg_lo:[1,0,0] neg_hi:[1,0,0]
	v_lshlrev_b32_e32 v20, 16, v10
	v_and_b32_e32 v21, 0xffff0000, v10
	v_lshlrev_b32_e32 v10, 16, v11
	v_and_b32_e32 v11, 0xffff0000, v11
	v_lshlrev_b32_e32 v22, 16, v18
	v_and_b32_e32 v23, 0xffff0000, v18
	v_lshlrev_b32_e32 v18, 16, v19
	v_and_b32_e32 v19, 0xffff0000, v19
	v_pk_fma_f32 v[10:11], v[28:29], v[18:19], v[10:11]
	v_pk_fma_f32 v[18:19], v[150:151], v[22:23], v[20:21] neg_lo:[1,0,0] neg_hi:[1,0,0]
	v_pk_mul_f32 v[4:5], v[4:5], v[16:17]
	v_fma_f32 v20, v18, v18, 0
	v_fmac_f32_e32 v20, v16, v16
	v_fmac_f32_e32 v20, v19, v19
	v_fmac_f32_e32 v20, v17, v17
	v_fmac_f32_e32 v20, v10, v10
	v_fmac_f32_e32 v20, v8, v8
	v_fmac_f32_e32 v20, v11, v11
	v_fmac_f32_e32 v20, v9, v9
	v_pk_mul_f32 v[0:1], v[0:1], v[18:19]
	v_pk_mul_f32 v[2:3], v[2:3], v[10:11]
	v_pk_mul_f32 v[6:7], v[6:7], v[8:9]
	s_waitcnt lgkmcnt(0)
	s_nop 1
	v_add_f32_dpp v20, v20, v20 quad_perm:[1,0,3,2] row_mask:0xf bank_mask:0xf
	s_waitcnt lgkmcnt(0)
	s_nop 1
	v_add_f32_dpp v20, v20, v20 quad_perm:[2,3,0,1] row_mask:0xf bank_mask:0xf
	s_waitcnt lgkmcnt(0)
	s_nop 1
	v_add_f32_dpp v20, v20, v20 row_half_mirror row_mask:0xf bank_mask:0xf
	s_waitcnt lgkmcnt(0)
	s_nop 1
	v_add_f32_dpp v20, v20, v20 row_mirror row_mask:0xf bank_mask:0xf
	ds_bpermute_b32 v21, v161, v20
	s_waitcnt lgkmcnt(0)
	v_add_f32_e32 v20, v20, v21
	v_fmamk_f32 v20, v20, 0x3b800000, v218
	v_mul_f32_e32 v21, 0x4b800000, v20
	v_cmp_gt_f32_e32 vcc, s78, v20
	s_nop 1
	v_cndmask_b32_e32 v20, v20, v21, vcc
	v_rsq_f32_e32 v22, v20
	v_lshl_add_u64 v[20:21], v[34:35], 0, v[32:33]
	global_store_dwordx4 v[20:21], v[12:15], off
	s_nop 1
	v_mul_f32_e32 v12, 0x45800000, v22
	v_cndmask_b32_e32 v12, v22, v12, vcc
	v_mul_f32_e32 v12, 0x3f4ccccd, v12
	v_pk_mul_f32 v[4:5], v[4:5], v[12:13] op_sel_hi:[1,0]
	v_pk_mul_f32 v[8:9], v[2:3], v[12:13] op_sel_hi:[1,0]
	v_pk_mul_f32 v[2:3], v[0:1], v[12:13] op_sel_hi:[1,0]
	v_cvt_pk_bf16_f32 v0, v4, v5
	v_lshl_add_u64 v[4:5], v[34:35], 0, v[30:31]
	v_pk_mul_f32 v[6:7], v[6:7], v[12:13] op_sel_hi:[1,0]
	s_nop 0
	v_cvt_pk_bf16_f32 v1, v6, v7
	v_cvt_pk_bf16_f32 v2, v2, v3
	v_cvt_pk_bf16_f32 v3, v8, v9
	global_store_dwordx4 v[4:5], v[0:3], off
	s_cbranch_scc1 .LBB0_411
